# fused final norm: meeting counter replaced by negative-initialised row-sum slots that every wave polls (two workgroup barriers and one atomic round trip fewer per unit)
# baseline (speedup 1.0000x reference)
.LBB0_1131:
	s_lshl_b32 s0, s87, 9
	v_add_u32_e32 v0, s0, v230
	s_load_dwordx2 s[0:1], s[92:93], 0xd8
	v_lshlrev_b32_e32 v0, 3, v0
	v_mov_b32_e32 v2, 0xbf800000
	v_mov_b32_e32 v3, 0xbf800000
	s_waitcnt lgkmcnt(0)
	s_add_u32 s0, s0, 0x32a0000
	s_addc_u32 s1, s1, 0
	global_store_dwordx2 v0, v[2:3], s[0:1]
	s_waitcnt vmcnt(0)
	s_barrier
	s_mov_b64 s[0:1], exec
	v_readlane_b32 s2, v252, 2
	v_readlane_b32 s3, v252, 3
	s_and_b64 s[2:3], s[0:1], s[2:3]
	s_mov_b64 exec, s[2:3]
	s_cbranch_execz .LBB0_1183
	s_add_i32 s2, 0, 0x20040
	v_mov_b32_e32 v0, s2
	s_waitcnt vmcnt(0) expcnt(0) lgkmcnt(0)
	ds_read_b32 v2, v0
	s_add_i32 s2, 0, 0x20044
	v_mov_b32_e32 v0, s2
	ds_read_b32 v0, v0
	s_waitcnt lgkmcnt(1)
	v_cmp_ne_u32_e32 vcc, 0, v2
	s_cbranch_vccnz .LBB0_1147
	s_add_u32 s6, s88, 0x1000
	s_addc_u32 s7, s89, 0
	s_add_u32 s8, s88, 0x1100
	s_addc_u32 s9, s89, 0
	s_add_u32 s10, s88, 0x1200
	v_readlane_b32 s2, v252, 0
	s_addc_u32 s11, s89, 0
	s_mul_i32 s2, s91, s2
	s_add_u32 s12, s88, 0x1300
	s_mul_i32 s2, s2, s90
	s_addc_u32 s13, s89, 0
	s_mov_b32 s3, 1
	v_mov_b32_e32 v16, 0
	s_branch .LBB0_1135

.Lfn_nosw_p14:
	s_mov_b32 s27, 0
.Lfn_poll_p14:
	global_load_dwordx4 v[156:159], v144, s[20:21] sc1
	global_load_dwordx4 v[160:163], v144, s[20:21] offset:256 sc1
	global_load_dwordx4 v[164:167], v144, s[20:21] offset:512 sc1
	global_load_dwordx4 v[168:171], v144, s[20:21] offset:768 sc1
	global_load_dwordx4 v[232:235], v144, s[20:21] offset:2048 sc1
	global_load_dwordx4 v[236:239], v144, s[20:21] offset:2304 sc1
	global_load_dwordx4 v[240:243], v144, s[20:21] offset:2560 sc1
	global_load_dwordx4 v[244:247], v144, s[20:21] offset:2816 sc1
	s_waitcnt vmcnt(0)
	v_or3_b32 v250, v156, v157, v158
	v_or3_b32 v250, v250, v159, v160
	v_or3_b32 v250, v250, v161, v162
	v_or3_b32 v250, v250, v163, v164
	v_or3_b32 v250, v250, v165, v166
	v_or3_b32 v250, v250, v167, v168
	v_or3_b32 v250, v250, v169, v170
	v_or3_b32 v250, v250, v171, v232
	v_or3_b32 v250, v250, v233, v234
	v_or3_b32 v250, v250, v235, v236
	v_or3_b32 v250, v250, v237, v238
	v_or3_b32 v250, v250, v239, v240
	v_or3_b32 v250, v250, v241, v242
	v_or3_b32 v250, v250, v243, v244
	v_or3_b32 v250, v250, v245, v246
	v_or_b32_e32 v250, v250, v247
	v_cmp_gt_i32_e32 vcc, 0, v250
	s_add_i32 s27, s27, 1
	s_nop 1
	s_cbranch_vccz .Lfn_ok_p14
	s_sleep 1
	s_cmp_lt_u32 s27, 0x8000
	s_cbranch_scc1 .Lfn_poll_p14
.Lfn_ok_p14:
	v_add_f32_e32 v250, v156, v157
	v_add_f32_e32 v251, v158, v159
	v_add_f32_e32 v146, v250, v251
	v_add_f32_e32 v250, v160, v161
	v_add_f32_e32 v251, v162, v163
	v_add_f32_e32 v147, v250, v251
	v_add_f32_e32 v250, v164, v165
	v_add_f32_e32 v251, v166, v167
	v_add_f32_e32 v148, v250, v251
	v_add_f32_e32 v250, v168, v169
	v_add_f32_e32 v251, v170, v171
	v_add_f32_e32 v149, v250, v251
	v_add_f32_e32 v250, v232, v233
	v_add_f32_e32 v251, v234, v235
	v_add_f32_e32 v150, v250, v251
	v_add_f32_e32 v250, v236, v237
	v_add_f32_e32 v251, v238, v239
	v_add_f32_e32 v151, v250, v251
	v_add_f32_e32 v250, v240, v241
	v_add_f32_e32 v251, v242, v243
	v_add_f32_e32 v152, v250, v251
	v_add_f32_e32 v250, v244, v245
	v_add_f32_e32 v251, v246, v247
	v_add_f32_e32 v153, v250, v251
	v_mov_b32_e32 v216, 0x358637bd
	v_mov_b32_e32 v217, 0x260
	s_mov_b32 s16, 0xf800000
	v_fmamk_f32 v146, v146, 0x3a800000, v216
	v_mul_f32_e32 v156, 0x4f800000, v146
	v_cmp_gt_f32_e32 vcc, s16, v146
	s_nop 1
	v_cndmask_b32_e32 v146, v146, v156, vcc
	v_sqrt_f32_e32 v157, v146
	s_nop 1
	v_add_u32_e32 v158, -1, v157
	v_add_u32_e32 v159, 1, v157
	v_fma_f32 v160, -v158, v157, v146
	v_fma_f32 v161, -v159, v157, v146
	v_cmp_ge_f32_e64 s[26:27], 0, v160
	s_nop 1
	v_cndmask_b32_e64 v157, v157, v158, s[26:27]
	v_cmp_lt_f32_e64 s[26:27], 0, v161
	s_nop 1
	v_cndmask_b32_e64 v157, v157, v159, s[26:27]
	v_mul_f32_e32 v158, 0x37800000, v157
	v_cndmask_b32_e32 v157, v157, v158, vcc
	v_cmp_class_f32_e32 vcc, v146, v217
	s_nop 1
	v_cndmask_b32_e32 v146, v157, v146, vcc
	v_div_scale_f32 v156, s[26:27], v146, v146, 1.0
	v_rcp_f32_e32 v157, v156
	v_div_scale_f32 v158, vcc, 1.0, v146, 1.0
	v_fma_f32 v159, -v156, v157, 1.0
	v_fmac_f32_e32 v157, v159, v157
	v_mul_f32_e32 v159, v158, v157
	v_fma_f32 v160, -v156, v159, v158
	v_fmac_f32_e32 v159, v160, v157
	v_fma_f32 v156, -v156, v159, v158
	v_div_fmas_f32 v159, v156, v157, v159
	v_div_fixup_f32 v200, v159, v146, 1.0
	v_fmamk_f32 v147, v147, 0x3a800000, v216
	v_mul_f32_e32 v156, 0x4f800000, v147
	v_cmp_gt_f32_e32 vcc, s16, v147
	s_nop 1
	v_cndmask_b32_e32 v147, v147, v156, vcc
	v_sqrt_f32_e32 v157, v147
	s_nop 1
	v_add_u32_e32 v158, -1, v157
	v_add_u32_e32 v159, 1, v157
	v_fma_f32 v160, -v158, v157, v147
	v_fma_f32 v161, -v159, v157, v147
	v_cmp_ge_f32_e64 s[26:27], 0, v160
	s_nop 1
	v_cndmask_b32_e64 v157, v157, v158, s[26:27]
	v_cmp_lt_f32_e64 s[26:27], 0, v161
	s_nop 1
	v_cndmask_b32_e64 v157, v157, v159, s[26:27]
	v_mul_f32_e32 v158, 0x37800000, v157
	v_cndmask_b32_e32 v157, v157, v158, vcc
	v_cmp_class_f32_e32 vcc, v147, v217
	s_nop 1
	v_cndmask_b32_e32 v147, v157, v147, vcc
	v_div_scale_f32 v156, s[26:27], v147, v147, 1.0
	v_rcp_f32_e32 v157, v156
	v_div_scale_f32 v158, vcc, 1.0, v147, 1.0
	v_fma_f32 v159, -v156, v157, 1.0
	v_fmac_f32_e32 v157, v159, v157
	v_mul_f32_e32 v159, v158, v157
	v_fma_f32 v160, -v156, v159, v158
	v_fmac_f32_e32 v159, v160, v157
	v_fma_f32 v156, -v156, v159, v158
	v_div_fmas_f32 v159, v156, v157, v159
	v_div_fixup_f32 v202, v159, v147, 1.0
	v_fmamk_f32 v148, v148, 0x3a800000, v216
	v_mul_f32_e32 v156, 0x4f800000, v148
	v_cmp_gt_f32_e32 vcc, s16, v148
	s_nop 1
	v_cndmask_b32_e32 v148, v148, v156, vcc
	v_sqrt_f32_e32 v157, v148
	s_nop 1
	v_add_u32_e32 v158, -1, v157
	v_add_u32_e32 v159, 1, v157
	v_fma_f32 v160, -v158, v157, v148
	v_fma_f32 v161, -v159, v157, v148
	v_cmp_ge_f32_e64 s[26:27], 0, v160
	s_nop 1
	v_cndmask_b32_e64 v157, v157, v158, s[26:27]
	v_cmp_lt_f32_e64 s[26:27], 0, v161
	s_nop 1
	v_cndmask_b32_e64 v157, v157, v159, s[26:27]
	v_mul_f32_e32 v158, 0x37800000, v157
	v_cndmask_b32_e32 v157, v157, v158, vcc
	v_cmp_class_f32_e32 vcc, v148, v217
	s_nop 1
	v_cndmask_b32_e32 v148, v157, v148, vcc
	v_div_scale_f32 v156, s[26:27], v148, v148, 1.0
	v_rcp_f32_e32 v157, v156
	v_div_scale_f32 v158, vcc, 1.0, v148, 1.0
	v_fma_f32 v159, -v156, v157, 1.0
	v_fmac_f32_e32 v157, v159, v157
	v_mul_f32_e32 v159, v158, v157
	v_fma_f32 v160, -v156, v159, v158
	v_fmac_f32_e32 v159, v160, v157
	v_fma_f32 v156, -v156, v159, v158
	v_div_fmas_f32 v159, v156, v157, v159
	v_div_fixup_f32 v204, v159, v148, 1.0
	v_fmamk_f32 v149, v149, 0x3a800000, v216
	v_mul_f32_e32 v156, 0x4f800000, v149
	v_cmp_gt_f32_e32 vcc, s16, v149
	s_nop 1
	v_cndmask_b32_e32 v149, v149, v156, vcc
	v_sqrt_f32_e32 v157, v149
	s_nop 1
	v_add_u32_e32 v158, -1, v157
	v_add_u32_e32 v159, 1, v157
	v_fma_f32 v160, -v158, v157, v149
	v_fma_f32 v161, -v159, v157, v149
	v_cmp_ge_f32_e64 s[26:27], 0, v160
	s_nop 1
	v_cndmask_b32_e64 v157, v157, v158, s[26:27]
	v_cmp_lt_f32_e64 s[26:27], 0, v161
	s_nop 1
	v_cndmask_b32_e64 v157, v157, v159, s[26:27]
	v_mul_f32_e32 v158, 0x37800000, v157
	v_cndmask_b32_e32 v157, v157, v158, vcc
	v_cmp_class_f32_e32 vcc, v149, v217
	s_nop 1
	v_cndmask_b32_e32 v149, v157, v149, vcc
	v_div_scale_f32 v156, s[26:27], v149, v149, 1.0
	v_rcp_f32_e32 v157, v156
	v_div_scale_f32 v158, vcc, 1.0, v149, 1.0
	v_fma_f32 v159, -v156, v157, 1.0
	v_fmac_f32_e32 v157, v159, v157
	v_mul_f32_e32 v159, v158, v157
	v_fma_f32 v160, -v156, v159, v158
	v_fmac_f32_e32 v159, v160, v157
	v_fma_f32 v156, -v156, v159, v158
	v_div_fmas_f32 v159, v156, v157, v159
	v_div_fixup_f32 v206, v159, v149, 1.0
	v_fmamk_f32 v150, v150, 0x3a800000, v216
	v_mul_f32_e32 v156, 0x4f800000, v150
	v_cmp_gt_f32_e32 vcc, s16, v150
	s_nop 1
	v_cndmask_b32_e32 v150, v150, v156, vcc
	v_sqrt_f32_e32 v157, v150
	s_nop 1
	v_add_u32_e32 v158, -1, v157
	v_add_u32_e32 v159, 1, v157
	v_fma_f32 v160, -v158, v157, v150
	v_fma_f32 v161, -v159, v157, v150
	v_cmp_ge_f32_e64 s[26:27], 0, v160
	s_nop 1
	v_cndmask_b32_e64 v157, v157, v158, s[26:27]
	v_cmp_lt_f32_e64 s[26:27], 0, v161
	s_nop 1
	v_cndmask_b32_e64 v157, v157, v159, s[26:27]
	v_mul_f32_e32 v158, 0x37800000, v157
	v_cndmask_b32_e32 v157, v157, v158, vcc
	v_cmp_class_f32_e32 vcc, v150, v217
	s_nop 1
	v_cndmask_b32_e32 v150, v157, v150, vcc
	v_div_scale_f32 v156, s[26:27], v150, v150, 1.0
	v_rcp_f32_e32 v157, v156
	v_div_scale_f32 v158, vcc, 1.0, v150, 1.0
	v_fma_f32 v159, -v156, v157, 1.0
	v_fmac_f32_e32 v157, v159, v157
	v_mul_f32_e32 v159, v158, v157
	v_fma_f32 v160, -v156, v159, v158
	v_fmac_f32_e32 v159, v160, v157
	v_fma_f32 v156, -v156, v159, v158
	v_div_fmas_f32 v159, v156, v157, v159
	v_div_fixup_f32 v208, v159, v150, 1.0
	v_fmamk_f32 v151, v151, 0x3a800000, v216
	v_mul_f32_e32 v156, 0x4f800000, v151
	v_cmp_gt_f32_e32 vcc, s16, v151
	s_nop 1
	v_cndmask_b32_e32 v151, v151, v156, vcc
	v_sqrt_f32_e32 v157, v151
	s_nop 1
	v_add_u32_e32 v158, -1, v157
	v_add_u32_e32 v159, 1, v157
	v_fma_f32 v160, -v158, v157, v151
	v_fma_f32 v161, -v159, v157, v151
	v_cmp_ge_f32_e64 s[26:27], 0, v160
	s_nop 1
	v_cndmask_b32_e64 v157, v157, v158, s[26:27]
	v_cmp_lt_f32_e64 s[26:27], 0, v161
	s_nop 1
	v_cndmask_b32_e64 v157, v157, v159, s[26:27]
	v_mul_f32_e32 v158, 0x37800000, v157
	v_cndmask_b32_e32 v157, v157, v158, vcc
	v_cmp_class_f32_e32 vcc, v151, v217
	s_nop 1
	v_cndmask_b32_e32 v151, v157, v151, vcc
	v_div_scale_f32 v156, s[26:27], v151, v151, 1.0
	v_rcp_f32_e32 v157, v156
	v_div_scale_f32 v158, vcc, 1.0, v151, 1.0
	v_fma_f32 v159, -v156, v157, 1.0
	v_fmac_f32_e32 v157, v159, v157
	v_mul_f32_e32 v159, v158, v157
	v_fma_f32 v160, -v156, v159, v158
	v_fmac_f32_e32 v159, v160, v157
	v_fma_f32 v156, -v156, v159, v158
	v_div_fmas_f32 v159, v156, v157, v159
	v_div_fixup_f32 v210, v159, v151, 1.0
	v_fmamk_f32 v152, v152, 0x3a800000, v216
	v_mul_f32_e32 v156, 0x4f800000, v152
	v_cmp_gt_f32_e32 vcc, s16, v152
	s_nop 1
	v_cndmask_b32_e32 v152, v152, v156, vcc
	v_sqrt_f32_e32 v157, v152
	s_nop 1
	v_add_u32_e32 v158, -1, v157
	v_add_u32_e32 v159, 1, v157
	v_fma_f32 v160, -v158, v157, v152
	v_fma_f32 v161, -v159, v157, v152
	v_cmp_ge_f32_e64 s[26:27], 0, v160
	s_nop 1
	v_cndmask_b32_e64 v157, v157, v158, s[26:27]
	v_cmp_lt_f32_e64 s[26:27], 0, v161
	s_nop 1
	v_cndmask_b32_e64 v157, v157, v159, s[26:27]
	v_mul_f32_e32 v158, 0x37800000, v157
	v_cndmask_b32_e32 v157, v157, v158, vcc
	v_cmp_class_f32_e32 vcc, v152, v217
	s_nop 1
	v_cndmask_b32_e32 v152, v157, v152, vcc
	v_div_scale_f32 v156, s[26:27], v152, v152, 1.0
	v_rcp_f32_e32 v157, v156
	v_div_scale_f32 v158, vcc, 1.0, v152, 1.0
	v_fma_f32 v159, -v156, v157, 1.0
	v_fmac_f32_e32 v157, v159, v157
	v_mul_f32_e32 v159, v158, v157
	v_fma_f32 v160, -v156, v159, v158
	v_fmac_f32_e32 v159, v160, v157
	v_fma_f32 v156, -v156, v159, v158
	v_div_fmas_f32 v159, v156, v157, v159
	v_div_fixup_f32 v212, v159, v152, 1.0
	v_fmamk_f32 v153, v153, 0x3a800000, v216
	v_mul_f32_e32 v156, 0x4f800000, v153
	v_cmp_gt_f32_e32 vcc, s16, v153
	s_nop 1
	v_cndmask_b32_e32 v153, v153, v156, vcc
	v_sqrt_f32_e32 v157, v153
	s_nop 1
	v_add_u32_e32 v158, -1, v157
	v_add_u32_e32 v159, 1, v157
	v_fma_f32 v160, -v158, v157, v153
	v_fma_f32 v161, -v159, v157, v153
	v_cmp_ge_f32_e64 s[26:27], 0, v160
	s_nop 1
	v_cndmask_b32_e64 v157, v157, v158, s[26:27]
	v_cmp_lt_f32_e64 s[26:27], 0, v161
	s_nop 1
	v_cndmask_b32_e64 v157, v157, v159, s[26:27]
	v_mul_f32_e32 v158, 0x37800000, v157
	v_cndmask_b32_e32 v157, v157, v158, vcc
	v_cmp_class_f32_e32 vcc, v153, v217
	s_nop 1
	v_cndmask_b32_e32 v153, v157, v153, vcc
	v_div_scale_f32 v156, s[26:27], v153, v153, 1.0
	v_rcp_f32_e32 v157, v156
	v_div_scale_f32 v158, vcc, 1.0, v153, 1.0
	v_fma_f32 v159, -v156, v157, 1.0
	v_fmac_f32_e32 v157, v159, v157
	v_mul_f32_e32 v159, v158, v157
	v_fma_f32 v160, -v156, v159, v158
	v_fmac_f32_e32 v159, v160, v157
	v_fma_f32 v156, -v156, v159, v158
	v_div_fmas_f32 v159, v156, v157, v159
	v_div_fixup_f32 v214, v159, v153, 1.0
	v_pk_mul_f32 v[124:125], v[124:125], v[200:201] op_sel_hi:[1,0]
	v_pk_mul_f32 v[126:127], v[126:127], v[200:201] op_sel_hi:[1,0]
	v_pk_mul_f32 v[124:125], v[184:185], v[124:125]
	v_pk_mul_f32 v[126:127], v[186:187], v[126:127]
	v_pk_mul_f32 v[96:97], v[96:97], v[200:201] op_sel_hi:[1,0]
	v_pk_mul_f32 v[98:99], v[98:99], v[200:201] op_sel_hi:[1,0]
	v_pk_mul_f32 v[96:97], v[188:189], v[96:97]
	v_pk_mul_f32 v[98:99], v[190:191], v[98:99]
	v_pk_mul_f32 v[64:65], v[64:65], v[200:201] op_sel_hi:[1,0]
	v_pk_mul_f32 v[66:67], v[66:67], v[200:201] op_sel_hi:[1,0]
	v_pk_mul_f32 v[64:65], v[192:193], v[64:65]
	v_pk_mul_f32 v[66:67], v[194:195], v[66:67]
	v_pk_mul_f32 v[44:45], v[44:45], v[200:201] op_sel_hi:[1,0]
	v_pk_mul_f32 v[46:47], v[46:47], v[200:201] op_sel_hi:[1,0]
	v_pk_mul_f32 v[44:45], v[196:197], v[44:45]
	v_pk_mul_f32 v[46:47], v[198:199], v[46:47]
	global_store_dwordx4 v128, v[124:127], s[8:9]
	global_store_dwordx4 v128, v[96:99], s[8:9] offset:64
	global_store_dwordx4 v128, v[64:67], s[8:9] offset:512
	global_store_dwordx4 v128, v[44:47], s[8:9] offset:576
	v_pk_mul_f32 v[120:121], v[120:121], v[202:203] op_sel_hi:[1,0]
	v_pk_mul_f32 v[122:123], v[122:123], v[202:203] op_sel_hi:[1,0]
	v_pk_mul_f32 v[120:121], v[184:185], v[120:121]
	v_pk_mul_f32 v[122:123], v[186:187], v[122:123]
	v_pk_mul_f32 v[88:89], v[88:89], v[202:203] op_sel_hi:[1,0]
	v_pk_mul_f32 v[90:91], v[90:91], v[202:203] op_sel_hi:[1,0]
	v_pk_mul_f32 v[88:89], v[188:189], v[88:89]
	v_pk_mul_f32 v[90:91], v[190:191], v[90:91]
	v_pk_mul_f32 v[56:57], v[56:57], v[202:203] op_sel_hi:[1,0]
	v_pk_mul_f32 v[58:59], v[58:59], v[202:203] op_sel_hi:[1,0]
	v_pk_mul_f32 v[56:57], v[192:193], v[56:57]
	v_pk_mul_f32 v[58:59], v[194:195], v[58:59]
	v_pk_mul_f32 v[36:37], v[36:37], v[202:203] op_sel_hi:[1,0]
	v_pk_mul_f32 v[38:39], v[38:39], v[202:203] op_sel_hi:[1,0]
	v_pk_mul_f32 v[36:37], v[196:197], v[36:37]
	v_pk_mul_f32 v[38:39], v[198:199], v[38:39]
	global_store_dwordx4 v129, v[120:123], s[8:9]
	global_store_dwordx4 v129, v[88:91], s[8:9] offset:64
	global_store_dwordx4 v129, v[56:59], s[8:9] offset:512
	global_store_dwordx4 v129, v[36:39], s[8:9] offset:576
	v_pk_mul_f32 v[116:117], v[116:117], v[204:205] op_sel_hi:[1,0]
	v_pk_mul_f32 v[118:119], v[118:119], v[204:205] op_sel_hi:[1,0]
	v_pk_mul_f32 v[116:117], v[184:185], v[116:117]
	v_pk_mul_f32 v[118:119], v[186:187], v[118:119]
	v_pk_mul_f32 v[84:85], v[84:85], v[204:205] op_sel_hi:[1,0]
	v_pk_mul_f32 v[86:87], v[86:87], v[204:205] op_sel_hi:[1,0]
	v_pk_mul_f32 v[84:85], v[188:189], v[84:85]
	v_pk_mul_f32 v[86:87], v[190:191], v[86:87]
	v_pk_mul_f32 v[52:53], v[52:53], v[204:205] op_sel_hi:[1,0]
	v_pk_mul_f32 v[54:55], v[54:55], v[204:205] op_sel_hi:[1,0]
	v_pk_mul_f32 v[52:53], v[192:193], v[52:53]
	v_pk_mul_f32 v[54:55], v[194:195], v[54:55]
	v_pk_mul_f32 v[28:29], v[28:29], v[204:205] op_sel_hi:[1,0]
	v_pk_mul_f32 v[30:31], v[30:31], v[204:205] op_sel_hi:[1,0]
	v_pk_mul_f32 v[28:29], v[196:197], v[28:29]
	v_pk_mul_f32 v[30:31], v[198:199], v[30:31]
	global_store_dwordx4 v130, v[116:119], s[8:9]
	global_store_dwordx4 v130, v[84:87], s[8:9] offset:64
	global_store_dwordx4 v130, v[52:55], s[8:9] offset:512
	global_store_dwordx4 v130, v[28:31], s[8:9] offset:576
	v_pk_mul_f32 v[112:113], v[112:113], v[206:207] op_sel_hi:[1,0]
	v_pk_mul_f32 v[114:115], v[114:115], v[206:207] op_sel_hi:[1,0]
	v_pk_mul_f32 v[112:113], v[184:185], v[112:113]
	v_pk_mul_f32 v[114:115], v[186:187], v[114:115]
	v_pk_mul_f32 v[80:81], v[80:81], v[206:207] op_sel_hi:[1,0]
	v_pk_mul_f32 v[82:83], v[82:83], v[206:207] op_sel_hi:[1,0]
	v_pk_mul_f32 v[80:81], v[188:189], v[80:81]
	v_pk_mul_f32 v[82:83], v[190:191], v[82:83]
	v_pk_mul_f32 v[48:49], v[48:49], v[206:207] op_sel_hi:[1,0]
	v_pk_mul_f32 v[50:51], v[50:51], v[206:207] op_sel_hi:[1,0]
	v_pk_mul_f32 v[48:49], v[192:193], v[48:49]
	v_pk_mul_f32 v[50:51], v[194:195], v[50:51]
	v_pk_mul_f32 v[20:21], v[20:21], v[206:207] op_sel_hi:[1,0]
	v_pk_mul_f32 v[22:23], v[22:23], v[206:207] op_sel_hi:[1,0]
	v_pk_mul_f32 v[20:21], v[196:197], v[20:21]
	v_pk_mul_f32 v[22:23], v[198:199], v[22:23]
	global_store_dwordx4 v131, v[112:115], s[8:9]
	global_store_dwordx4 v131, v[80:83], s[8:9] offset:64
	global_store_dwordx4 v131, v[48:51], s[8:9] offset:512
	global_store_dwordx4 v131, v[20:23], s[8:9] offset:576
	v_pk_mul_f32 v[108:109], v[108:109], v[208:209] op_sel_hi:[1,0]
	v_pk_mul_f32 v[110:111], v[110:111], v[208:209] op_sel_hi:[1,0]
	v_pk_mul_f32 v[108:109], v[184:185], v[108:109]
	v_pk_mul_f32 v[110:111], v[186:187], v[110:111]
	v_pk_mul_f32 v[76:77], v[76:77], v[208:209] op_sel_hi:[1,0]
	v_pk_mul_f32 v[78:79], v[78:79], v[208:209] op_sel_hi:[1,0]
	v_pk_mul_f32 v[76:77], v[188:189], v[76:77]
	v_pk_mul_f32 v[78:79], v[190:191], v[78:79]
	v_pk_mul_f32 v[40:41], v[40:41], v[208:209] op_sel_hi:[1,0]
	v_pk_mul_f32 v[42:43], v[42:43], v[208:209] op_sel_hi:[1,0]
	v_pk_mul_f32 v[40:41], v[192:193], v[40:41]
	v_pk_mul_f32 v[42:43], v[194:195], v[42:43]
	v_pk_mul_f32 v[12:13], v[12:13], v[208:209] op_sel_hi:[1,0]
	v_pk_mul_f32 v[14:15], v[14:15], v[208:209] op_sel_hi:[1,0]
	v_pk_mul_f32 v[12:13], v[196:197], v[12:13]
	v_pk_mul_f32 v[14:15], v[198:199], v[14:15]
	global_store_dwordx4 v132, v[108:111], s[8:9]
	global_store_dwordx4 v132, v[76:79], s[8:9] offset:64
	global_store_dwordx4 v132, v[40:43], s[8:9] offset:512
	global_store_dwordx4 v132, v[12:15], s[8:9] offset:576
	v_pk_mul_f32 v[104:105], v[104:105], v[210:211] op_sel_hi:[1,0]
	v_pk_mul_f32 v[106:107], v[106:107], v[210:211] op_sel_hi:[1,0]
	v_pk_mul_f32 v[104:105], v[184:185], v[104:105]
	v_pk_mul_f32 v[106:107], v[186:187], v[106:107]
	v_pk_mul_f32 v[72:73], v[72:73], v[210:211] op_sel_hi:[1,0]
	v_pk_mul_f32 v[74:75], v[74:75], v[210:211] op_sel_hi:[1,0]
	v_pk_mul_f32 v[72:73], v[188:189], v[72:73]
	v_pk_mul_f32 v[74:75], v[190:191], v[74:75]
	v_pk_mul_f32 v[32:33], v[32:33], v[210:211] op_sel_hi:[1,0]
	v_pk_mul_f32 v[34:35], v[34:35], v[210:211] op_sel_hi:[1,0]
	v_pk_mul_f32 v[32:33], v[192:193], v[32:33]
	v_pk_mul_f32 v[34:35], v[194:195], v[34:35]
	v_pk_mul_f32 v[8:9], v[8:9], v[210:211] op_sel_hi:[1,0]
	v_pk_mul_f32 v[10:11], v[10:11], v[210:211] op_sel_hi:[1,0]
	v_pk_mul_f32 v[8:9], v[196:197], v[8:9]
	v_pk_mul_f32 v[10:11], v[198:199], v[10:11]
	global_store_dwordx4 v133, v[104:107], s[8:9]
	global_store_dwordx4 v133, v[72:75], s[8:9] offset:64
	global_store_dwordx4 v133, v[32:35], s[8:9] offset:512
	global_store_dwordx4 v133, v[8:11], s[8:9] offset:576
	v_pk_mul_f32 v[100:101], v[100:101], v[212:213] op_sel_hi:[1,0]
	v_pk_mul_f32 v[102:103], v[102:103], v[212:213] op_sel_hi:[1,0]
	v_pk_mul_f32 v[100:101], v[184:185], v[100:101]
	v_pk_mul_f32 v[102:103], v[186:187], v[102:103]
	v_pk_mul_f32 v[68:69], v[68:69], v[212:213] op_sel_hi:[1,0]
	v_pk_mul_f32 v[70:71], v[70:71], v[212:213] op_sel_hi:[1,0]
	v_pk_mul_f32 v[68:69], v[188:189], v[68:69]
	v_pk_mul_f32 v[70:71], v[190:191], v[70:71]
	v_pk_mul_f32 v[24:25], v[24:25], v[212:213] op_sel_hi:[1,0]
	v_pk_mul_f32 v[26:27], v[26:27], v[212:213] op_sel_hi:[1,0]
	v_pk_mul_f32 v[24:25], v[192:193], v[24:25]
	v_pk_mul_f32 v[26:27], v[194:195], v[26:27]
	v_pk_mul_f32 v[4:5], v[4:5], v[212:213] op_sel_hi:[1,0]
	v_pk_mul_f32 v[6:7], v[6:7], v[212:213] op_sel_hi:[1,0]
	v_pk_mul_f32 v[4:5], v[196:197], v[4:5]
	v_pk_mul_f32 v[6:7], v[198:199], v[6:7]
	global_store_dwordx4 v134, v[100:103], s[8:9]
	global_store_dwordx4 v134, v[68:71], s[8:9] offset:64
	global_store_dwordx4 v134, v[24:27], s[8:9] offset:512
	global_store_dwordx4 v134, v[4:7], s[8:9] offset:576
	v_pk_mul_f32 v[92:93], v[92:93], v[214:215] op_sel_hi:[1,0]
	v_pk_mul_f32 v[94:95], v[94:95], v[214:215] op_sel_hi:[1,0]
	v_pk_mul_f32 v[92:93], v[184:185], v[92:93]
	v_pk_mul_f32 v[94:95], v[186:187], v[94:95]
	v_pk_mul_f32 v[60:61], v[60:61], v[214:215] op_sel_hi:[1,0]
	v_pk_mul_f32 v[62:63], v[62:63], v[214:215] op_sel_hi:[1,0]
	v_pk_mul_f32 v[60:61], v[188:189], v[60:61]
	v_pk_mul_f32 v[62:63], v[190:191], v[62:63]
	v_pk_mul_f32 v[16:17], v[16:17], v[214:215] op_sel_hi:[1,0]
	v_pk_mul_f32 v[18:19], v[18:19], v[214:215] op_sel_hi:[1,0]
	v_pk_mul_f32 v[16:17], v[192:193], v[16:17]
	v_pk_mul_f32 v[18:19], v[194:195], v[18:19]
	v_pk_mul_f32 v[0:1], v[0:1], v[214:215] op_sel_hi:[1,0]
	v_pk_mul_f32 v[2:3], v[2:3], v[214:215] op_sel_hi:[1,0]
	v_pk_mul_f32 v[0:1], v[196:197], v[0:1]
	v_pk_mul_f32 v[2:3], v[198:199], v[2:3]
	global_store_dwordx4 v135, v[92:95], s[8:9]
	global_store_dwordx4 v135, v[60:63], s[8:9] offset:64
	global_store_dwordx4 v135, v[16:19], s[8:9] offset:512
	global_store_dwordx4 v135, v[0:3], s[8:9] offset:576
	s_mov_b64 s[30:31], -1
	s_and_b64 vcc, exec, s[4:5]
	s_cbranch_vccnz .LBB0_1399
	s_andn2_b64 vcc, exec, s[12:13]
	s_cbranch_vccnz .LBB0_1398
	s_barrier
	s_branch .LBB0_1398
